# hyena-latent items: static s_setprio 1 for waves 4-7 (reset at attention items)
# baseline (speedup 1.0000x reference)
.LBB0_972:
	s_setprio 0
	s_mov_b64 s[0:1], 0
	s_mov_b32 s26, 0x41800000
	s_cbranch_execnz .LBB0_1095
	s_branch .LBB0_1115

.LBB0_974:
	s_and_b64 vcc, exec, s[22:23]
	s_cbranch_vccz .LBB0_1094
	v_readfirstlane_b32 s0, v179
	s_cmp_ge_u32 s0, 0x100
	s_cbranch_scc0 .Lp3h_np
	s_setprio 1
.Lp3h_np:
	s_ashr_i32 s51, s50, 31
	v_readlane_b32 s12, v254, 23
	s_lshl_b64 s[0:1], s[50:51], 2
	v_readlane_b32 s14, v254, 25
	v_readlane_b32 s15, v254, 26
	s_add_u32 s10, s14, s0
	s_addc_u32 s11, s15, s1
	v_readlane_b32 s13, v254, 24
	s_add_u32 s12, s10, 0x1800
	s_addc_u32 s13, s11, 0
	s_add_u32 s14, s10, 0x3000
	v_readlane_b32 s16, v254, 27
	s_addc_u32 s15, s11, 0
	v_readlane_b32 s17, v254, 28
	s_add_u32 s16, s16, s0
	v_readlane_b32 s18, v254, 29
	s_addc_u32 s17, s17, s1
	s_mul_i32 s6, s50, 0x8200
	v_readlane_b32 s0, v254, 57
	v_readlane_b32 s19, v254, 30
	s_mul_hi_i32 s7, s50, 0x8200
	v_readlane_b32 s1, v254, 58
	s_add_u32 s18, s0, s6
	v_mov_b32_e32 v0, v179
	v_readlane_b32 s20, v254, 31
	s_addc_u32 s19, s1, s7
	v_readlane_b32 s21, v254, 32
	s_add_u32 s20, s18, 0x30c0200
	v_lshl_add_u32 v138, v0, 5, 32
	s_mov_b64 s[40:41], s[58:59]
	s_addc_u32 s21, s19, 0
	v_add_u32_e32 v139, 0x10000, v138
	v_add_u32_e32 v140, 0x10010, v138
	v_add_u32_e32 v141, 0x14000, v138
	v_add_u32_e32 v142, 0x14010, v138
	v_add_u32_e32 v143, 0x18000, v138
	v_add_u32_e32 v144, 0x18010, v138
	v_add_u32_e32 v145, 0x1c000, v138
	v_add_u32_e32 v146, 0x1c010, v138
	s_mov_b32 s9, 0
	s_mov_b64 s[52:53], -1
	v_readlane_b32 s22, v254, 33
	v_readlane_b32 s23, v254, 34
	v_readlane_b32 s24, v254, 35
	v_readlane_b32 s25, v254, 36
	v_readlane_b32 s26, v254, 37
	v_readlane_b32 s27, v254, 38
	s_branch .LBB0_977
